# v57 + MoBA attention near-diagonal path: 32 relative-position LUT reads issued in two batches and masked in registers (no per-element exec mask / branch / LDS round trip)
# baseline (speedup 1.0000x reference)
; #define LAS __attribute__((address_space(3)))
; template <bool MOBA>
; __device__ __forceinline__ void attn_unit(LAS unsigned char* lds, const bf16_t* Qp, int ldq, const bf16_t* Kp, const bf16_t* Vp, int ldkv, bf16_t* Op, int ldo, int qt, const float* kmean, const float* relb, const int tid) {
;     ...
;             for (int kt = 0; kt < 8; ++kt) { sacc[kt] = (f32x4){0.f, 0.f, 0.f, 0.f};
; #pragma unroll
;                 for (int s = 0; s < 4; ++s) { const bf16x8 kf = *(const LAS bf16x8*)(lds + AT_KS + (kt * 16 + l15) * AT_PITCH + (quad * 8 + 32 * s) * 2); sacc[kt] = __builtin_amdgcn_mfma_f32_16x16x32_bf16(kf, qf[s], sacc[kt], 0, 0, 0); }
;                 if (kt & 1) __builtin_amdgcn_sched_barrier(0); }
;             float mx = -INFINITY; float ps = 0.f;
;             bool simple = !MOBA; float cbm = 0.f;
;             bool lsel = true;
;             if (MOBA) {
;                 const bool farb = (qt * 128 + w * 16) - (kr0 + 127) >= 127;
;                 lsel = (j == own) || ((mysel >> j) & 1u);
;                 simple = farb; cbm = lsel ? ((const LAS float*)(lds + AT_LUT))[127] : -INFINITY;
;             }
.LBB0_1178:
	s_lshr_b32 s10, s38, 1
	s_cmp_eq_u32 s10, s54
	s_cselect_b64 s[8:9], -1, 0
	s_lshl_b32 s10, 1, s10
	s_and_b32 s11, s10, s35
	s_cmp_lg_u32 s11, 0
	s_cselect_b64 s[28:29], -1, 0
	s_or_b64 s[28:29], s[8:9], s[28:29]
	s_andn2_b64 vcc, exec, s[28:29]
	s_cbranch_vccnz .LBB0_1254
	ds_read_b128 v[0:3], v194
	ds_read_b128 v[4:7], v194 offset:64
	ds_read_b128 v[8:11], v194 offset:4352
	ds_read_b128 v[12:15], v194 offset:4416
	ds_read_b128 v[16:19], v194 offset:128
	s_waitcnt lgkmcnt(4)
	v_mfma_f32_16x16x32_bf16 v[0:3], v[0:3], v[48:51], 0
	s_waitcnt lgkmcnt(3)
	v_mfma_f32_16x16x32_bf16 v[0:3], v[4:7], v[56:59], v[0:3]
	ds_read_b128 v[4:7], v194 offset:192
	s_waitcnt lgkmcnt(1)
	v_mfma_f32_16x16x32_bf16 v[0:3], v[16:19], v[60:63], v[0:3]
	v_mfma_f32_16x16x32_bf16 v[8:11], v[8:11], v[48:51], 0
	s_waitcnt lgkmcnt(0)
	v_mfma_f32_16x16x32_bf16 v[0:3], v[4:7], v[64:67], v[0:3]
	ds_read_b128 v[4:7], v194 offset:4480
	v_mfma_f32_16x16x32_bf16 v[8:11], v[12:15], v[56:59], v[8:11]
	ds_read_b128 v[12:15], v194 offset:4544
	s_waitcnt lgkmcnt(1)
	v_mfma_f32_16x16x32_bf16 v[4:7], v[4:7], v[60:63], v[8:11]
	s_waitcnt lgkmcnt(0)
	v_mfma_f32_16x16x32_bf16 v[4:7], v[12:15], v[64:67], v[4:7]
	s_nop 2
	ds_read_b128 v[8:11], v194 offset:8704
	ds_read_b128 v[12:15], v194 offset:8768
	ds_read_b128 v[16:19], v194 offset:13056
	ds_read_b128 v[20:23], v194 offset:13120
	ds_read_b128 v[24:27], v194 offset:8832
	s_waitcnt lgkmcnt(4)
	v_mfma_f32_16x16x32_bf16 v[8:11], v[8:11], v[48:51], 0
	s_waitcnt lgkmcnt(3)
	v_mfma_f32_16x16x32_bf16 v[8:11], v[12:15], v[56:59], v[8:11]
	ds_read_b128 v[12:15], v194 offset:8896
	s_waitcnt lgkmcnt(1)
	v_mfma_f32_16x16x32_bf16 v[8:11], v[24:27], v[60:63], v[8:11]
	v_mfma_f32_16x16x32_bf16 v[16:19], v[16:19], v[48:51], 0
	s_waitcnt lgkmcnt(0)
	v_mfma_f32_16x16x32_bf16 v[8:11], v[12:15], v[64:67], v[8:11]
	ds_read_b128 v[12:15], v194 offset:13184
	v_mfma_f32_16x16x32_bf16 v[16:19], v[20:23], v[56:59], v[16:19]
	ds_read_b128 v[20:23], v194 offset:13248
	s_waitcnt lgkmcnt(1)
	v_mfma_f32_16x16x32_bf16 v[12:15], v[12:15], v[60:63], v[16:19]
	s_waitcnt lgkmcnt(0)
	v_mfma_f32_16x16x32_bf16 v[12:15], v[20:23], v[64:67], v[12:15]
	s_nop 2
	ds_read_b128 v[16:19], v194 offset:17408
	ds_read_b128 v[20:23], v194 offset:17472
	ds_read_b128 v[24:27], v194 offset:21760
	ds_read_b128 v[28:31], v194 offset:21824
	ds_read_b128 v[166:169], v194 offset:17536
	s_waitcnt lgkmcnt(4)
	v_mfma_f32_16x16x32_bf16 v[16:19], v[16:19], v[48:51], 0
	s_waitcnt lgkmcnt(3)
	v_mfma_f32_16x16x32_bf16 v[16:19], v[20:23], v[56:59], v[16:19]
	ds_read_b128 v[20:23], v194 offset:17600
	s_waitcnt lgkmcnt(1)
	v_mfma_f32_16x16x32_bf16 v[16:19], v[166:169], v[60:63], v[16:19]
	v_mfma_f32_16x16x32_bf16 v[24:27], v[24:27], v[48:51], 0
	s_waitcnt lgkmcnt(0)
	v_mfma_f32_16x16x32_bf16 v[16:19], v[20:23], v[64:67], v[16:19]
	ds_read_b128 v[20:23], v194 offset:21888
	v_mfma_f32_16x16x32_bf16 v[24:27], v[28:31], v[56:59], v[24:27]
	ds_read_b128 v[28:31], v194 offset:21952
	s_waitcnt lgkmcnt(1)
	v_mfma_f32_16x16x32_bf16 v[20:23], v[20:23], v[60:63], v[24:27]
	s_waitcnt lgkmcnt(0)
	v_mfma_f32_16x16x32_bf16 v[20:23], v[28:31], v[64:67], v[20:23]
	s_nop 2
	ds_read_b128 v[24:27], v194 offset:26112
	ds_read_b128 v[28:31], v194 offset:26176
	ds_read_b128 v[166:169], v194 offset:30464
	ds_read_b128 v[206:209], v194 offset:30528
	ds_read_b128 v[210:213], v194 offset:26240
	s_waitcnt lgkmcnt(4)
	v_mfma_f32_16x16x32_bf16 v[24:27], v[24:27], v[48:51], 0
	s_waitcnt lgkmcnt(3)
	v_mfma_f32_16x16x32_bf16 v[24:27], v[28:31], v[56:59], v[24:27]
	ds_read_b128 v[28:31], v194 offset:26304
	s_waitcnt lgkmcnt(1)
	v_mfma_f32_16x16x32_bf16 v[24:27], v[210:213], v[60:63], v[24:27]
	v_mfma_f32_16x16x32_bf16 v[166:169], v[166:169], v[48:51], 0
	s_waitcnt lgkmcnt(0)
	v_mfma_f32_16x16x32_bf16 v[24:27], v[28:31], v[64:67], v[24:27]
	ds_read_b128 v[28:31], v194 offset:30592
	v_mfma_f32_16x16x32_bf16 v[166:169], v[206:209], v[56:59], v[166:169]
	ds_read_b128 v[206:209], v194 offset:30656
	s_waitcnt lgkmcnt(1)
	v_mfma_f32_16x16x32_bf16 v[28:31], v[28:31], v[60:63], v[166:169]
	s_waitcnt lgkmcnt(0)
	v_mfma_f32_16x16x32_bf16 v[28:31], v[206:209], v[64:67], v[28:31]
	v_and_b32_e32 v127, s10, v149
	v_cmp_ne_u32_e64 s[10:11], 0, v127
	s_or_b64 s[30:31], s[8:9], s[10:11]
	v_mov_b32_e32 v202, 0xff800000
	s_and_saveexec_b64 s[28:29], s[30:31]
	v_mov_b32_e32 v127, s46
	ds_read_b32 v202, v127
	s_or_b64 exec, exec, s[28:29]
	s_add_i32 s28, s37, s34
	s_addk_i32 s28, 0xff81
	s_cmpk_lt_i32 s28, 0x7f
	s_cselect_b64 s[28:29], -1, 0
	s_mov_b64 s[30:31], -1
	s_and_b64 vcc, exec, s[28:29]
	v_mov_b32_e32 v127, v31
	v_mov_b32_e32 v238, v30
	v_mov_b32_e32 v236, v29
	v_mov_b32_e32 v237, v28
	v_mov_b32_e32 v234, v27
	v_mov_b32_e32 v235, v26
	v_mov_b32_e32 v232, v25
	v_mov_b32_e32 v233, v24
	v_mov_b32_e32 v230, v23
	v_mov_b32_e32 v231, v22
	v_mov_b32_e32 v225, v21
	v_mov_b32_e32 v229, v20
	v_mov_b32_e32 v223, v19
	v_mov_b32_e32 v224, v18
	v_mov_b32_e32 v221, v17
	v_mov_b32_e32 v222, v16
	v_mov_b32_e32 v219, v15
	v_mov_b32_e32 v220, v14
	v_mov_b32_e32 v217, v13
	v_mov_b32_e32 v218, v12
	v_mov_b32_e32 v214, v11
	v_mov_b32_e32 v215, v10
	v_mov_b32_e32 v212, v9
	v_mov_b32_e32 v213, v8
	v_mov_b32_e32 v210, v7
	v_mov_b32_e32 v211, v6
	v_mov_b32_e32 v208, v5
	v_mov_b32_e32 v209, v4
	v_mov_b32_e32 v206, v3
	v_mov_b32_e32 v207, v2
	v_mov_b32_e32 v203, v1
	v_mov_b32_e32 v204, v0
	s_cbranch_vccz .LBB0_1247
; #define LAS __attribute__((address_space(3)))
; template <bool MOBA>
; __device__ __forceinline__ void attn_unit(LAS unsigned char* lds, const bf16_t* Qp, int ldq, const bf16_t* Kp, const bf16_t* Vp, int ldkv, bf16_t* Op, int ldo, int qt, const float* kmean, const float* relb, const int tid) {
;     ...
;                 const int qpos = qt * 128 + w * 16 + l15, kpos0 = kr0 + quad * 4;
; #pragma unroll
;                 for (int kt = 0; kt < 8; ++kt)
; #pragma unroll
;                     for (int i = 0; i < 4; ++i) { const int rel = qpos - (kpos0 + kt * 16 + i);
;                         const int ri = rel < 0 ? 0 : (rel > 127 ? 127 : rel); const float b = ((const LAS float*)(lds + AT_LUT))[ri];
;                         const bool valid = (j == own) ? (rel >= 0) : lsel;
;                         const float sv = valid ? sacc[kt][i] * sc2 + b : -INFINITY; sacc[kt][i] = sv; mx = fmaxf(mx, sv); }
	v_add_u32_e32 v166, s34, v199
	v_mov_b32_e32 v167, 0x15a00
	v_med3_i32 v168, v166, 0, v196
	v_lshl_add_u32 v168, v168, 2, v167
	ds_read_b32 v204, v168
	v_add_u32_e32 v168, -1, v166
	v_med3_i32 v168, v168, 0, v196
	v_lshl_add_u32 v168, v168, 2, v167
	ds_read_b32 v203, v168
	v_add_u32_e32 v168, -2, v166
	v_med3_i32 v168, v168, 0, v196
	v_lshl_add_u32 v168, v168, 2, v167
	ds_read_b32 v207, v168
	v_add_u32_e32 v168, -3, v166
	v_med3_i32 v168, v168, 0, v196
	v_lshl_add_u32 v168, v168, 2, v167
	ds_read_b32 v206, v168
	v_add_u32_e32 v168, -16, v166
	v_med3_i32 v168, v168, 0, v196
	v_lshl_add_u32 v168, v168, 2, v167
	ds_read_b32 v209, v168
	v_add_u32_e32 v168, -17, v166
	v_med3_i32 v168, v168, 0, v196
	v_lshl_add_u32 v168, v168, 2, v167
	ds_read_b32 v208, v168
	v_add_u32_e32 v168, -18, v166
	v_med3_i32 v168, v168, 0, v196
	v_lshl_add_u32 v168, v168, 2, v167
	ds_read_b32 v211, v168
	v_add_u32_e32 v168, -19, v166
	v_med3_i32 v168, v168, 0, v196
	v_lshl_add_u32 v168, v168, 2, v167
	ds_read_b32 v210, v168
	v_add_u32_e32 v168, -32, v166
	v_med3_i32 v168, v168, 0, v196
	v_lshl_add_u32 v168, v168, 2, v167
	ds_read_b32 v213, v168
	v_add_u32_e32 v168, -33, v166
	v_med3_i32 v168, v168, 0, v196
	v_lshl_add_u32 v168, v168, 2, v167
	ds_read_b32 v212, v168
	v_add_u32_e32 v168, -34, v166
	v_med3_i32 v168, v168, 0, v196
	v_lshl_add_u32 v168, v168, 2, v167
	ds_read_b32 v215, v168
	v_add_u32_e32 v168, -35, v166
	v_med3_i32 v168, v168, 0, v196
	v_lshl_add_u32 v168, v168, 2, v167
	ds_read_b32 v214, v168
	v_add_u32_e32 v168, -48, v166
	v_med3_i32 v168, v168, 0, v196
	v_lshl_add_u32 v168, v168, 2, v167
	ds_read_b32 v218, v168
	v_add_u32_e32 v168, -49, v166
	v_med3_i32 v168, v168, 0, v196
	v_lshl_add_u32 v168, v168, 2, v167
	ds_read_b32 v217, v168
	v_add_u32_e32 v168, -50, v166
	v_med3_i32 v168, v168, 0, v196
	v_lshl_add_u32 v168, v168, 2, v167
	ds_read_b32 v220, v168
	v_add_u32_e32 v168, -51, v166
	v_med3_i32 v168, v168, 0, v196
	v_lshl_add_u32 v168, v168, 2, v167
	ds_read_b32 v219, v168
	s_waitcnt lgkmcnt(0)
	v_add_u32_e32 v168, -64, v166
	v_med3_i32 v168, v168, 0, v196
	v_lshl_add_u32 v168, v168, 2, v167
	ds_read_b32 v222, v168
	v_add_u32_e32 v168, -65, v166
	v_med3_i32 v168, v168, 0, v196
	v_lshl_add_u32 v168, v168, 2, v167
	ds_read_b32 v221, v168
	v_add_u32_e32 v168, -66, v166
	v_med3_i32 v168, v168, 0, v196
	v_lshl_add_u32 v168, v168, 2, v167
	ds_read_b32 v224, v168
	v_add_u32_e32 v168, -67, v166
	v_med3_i32 v168, v168, 0, v196
	v_lshl_add_u32 v168, v168, 2, v167
	ds_read_b32 v223, v168
	v_add_u32_e32 v168, -80, v166
	v_med3_i32 v168, v168, 0, v196
	v_lshl_add_u32 v168, v168, 2, v167
	ds_read_b32 v229, v168
	v_add_u32_e32 v168, -81, v166
	v_med3_i32 v168, v168, 0, v196
	v_lshl_add_u32 v168, v168, 2, v167
	ds_read_b32 v225, v168
	v_add_u32_e32 v168, -82, v166
	v_med3_i32 v168, v168, 0, v196
	v_lshl_add_u32 v168, v168, 2, v167
	ds_read_b32 v231, v168
	v_add_u32_e32 v168, -83, v166
	v_med3_i32 v168, v168, 0, v196
	v_lshl_add_u32 v168, v168, 2, v167
	ds_read_b32 v230, v168
	v_add_u32_e32 v168, -96, v166
	v_med3_i32 v168, v168, 0, v196
	v_lshl_add_u32 v168, v168, 2, v167
	ds_read_b32 v233, v168
	v_add_u32_e32 v168, -97, v166
	v_med3_i32 v168, v168, 0, v196
	v_lshl_add_u32 v168, v168, 2, v167
	ds_read_b32 v232, v168
	v_add_u32_e32 v168, -98, v166
	v_med3_i32 v168, v168, 0, v196
	v_lshl_add_u32 v168, v168, 2, v167
	ds_read_b32 v235, v168
	v_add_u32_e32 v168, -99, v166
	v_med3_i32 v168, v168, 0, v196
	v_lshl_add_u32 v168, v168, 2, v167
	ds_read_b32 v234, v168
	v_add_u32_e32 v168, -112, v166
	v_med3_i32 v168, v168, 0, v196
	v_lshl_add_u32 v168, v168, 2, v167
	ds_read_b32 v237, v168
	v_add_u32_e32 v168, -113, v166
	v_med3_i32 v168, v168, 0, v196
	v_lshl_add_u32 v168, v168, 2, v167
	ds_read_b32 v236, v168
	v_add_u32_e32 v168, -114, v166
	v_med3_i32 v168, v168, 0, v196
	v_lshl_add_u32 v168, v168, 2, v167
	ds_read_b32 v238, v168
	v_add_u32_e32 v168, -115, v166
	v_med3_i32 v168, v168, 0, v196
	v_lshl_add_u32 v168, v168, 2, v167
	ds_read_b32 v127, v168
	v_mov_b32_e32 v167, 0xff800000
	s_and_b64 vcc, exec, s[8:9]
	s_cbranch_vccz .Llut_other
	v_fmac_f32_e32 v204, 0x3e0293ee, v0
	v_cmp_lt_i32_e32 vcc, -1, v166
	v_cndmask_b32_e32 v204, v167, v204, vcc
	v_fmac_f32_e32 v203, 0x3e0293ee, v1
	v_add_u32_e32 v168, -1, v166
	v_cmp_lt_i32_e32 vcc, -1, v168
	v_cndmask_b32_e32 v203, v167, v203, vcc
	v_fmac_f32_e32 v207, 0x3e0293ee, v2
	v_add_u32_e32 v168, -2, v166
	v_cmp_lt_i32_e32 vcc, -1, v168
	v_cndmask_b32_e32 v207, v167, v207, vcc
	v_fmac_f32_e32 v206, 0x3e0293ee, v3
	v_add_u32_e32 v168, -3, v166
	v_cmp_lt_i32_e32 vcc, -1, v168
	v_cndmask_b32_e32 v206, v167, v206, vcc
	v_fmac_f32_e32 v209, 0x3e0293ee, v4
	v_add_u32_e32 v168, -16, v166
	v_cmp_lt_i32_e32 vcc, -1, v168
	v_cndmask_b32_e32 v209, v167, v209, vcc
	v_fmac_f32_e32 v208, 0x3e0293ee, v5
	v_add_u32_e32 v168, -17, v166
	v_cmp_lt_i32_e32 vcc, -1, v168
	v_cndmask_b32_e32 v208, v167, v208, vcc
	v_fmac_f32_e32 v211, 0x3e0293ee, v6
	v_add_u32_e32 v168, -18, v166
	v_cmp_lt_i32_e32 vcc, -1, v168
	v_cndmask_b32_e32 v211, v167, v211, vcc
	v_fmac_f32_e32 v210, 0x3e0293ee, v7
	v_add_u32_e32 v168, -19, v166
	v_cmp_lt_i32_e32 vcc, -1, v168
	v_cndmask_b32_e32 v210, v167, v210, vcc
	v_fmac_f32_e32 v213, 0x3e0293ee, v8
	v_add_u32_e32 v168, -32, v166
	v_cmp_lt_i32_e32 vcc, -1, v168
	v_cndmask_b32_e32 v213, v167, v213, vcc
	v_fmac_f32_e32 v212, 0x3e0293ee, v9
	v_add_u32_e32 v168, -33, v166
	v_cmp_lt_i32_e32 vcc, -1, v168
	v_cndmask_b32_e32 v212, v167, v212, vcc
	v_fmac_f32_e32 v215, 0x3e0293ee, v10
	v_add_u32_e32 v168, -34, v166
	v_cmp_lt_i32_e32 vcc, -1, v168
	v_cndmask_b32_e32 v215, v167, v215, vcc
	v_fmac_f32_e32 v214, 0x3e0293ee, v11
	v_add_u32_e32 v168, -35, v166
	v_cmp_lt_i32_e32 vcc, -1, v168
	v_cndmask_b32_e32 v214, v167, v214, vcc
	v_fmac_f32_e32 v218, 0x3e0293ee, v12
	v_add_u32_e32 v168, -48, v166
	v_cmp_lt_i32_e32 vcc, -1, v168
	v_cndmask_b32_e32 v218, v167, v218, vcc
	v_fmac_f32_e32 v217, 0x3e0293ee, v13
	v_add_u32_e32 v168, -49, v166
	v_cmp_lt_i32_e32 vcc, -1, v168
	v_cndmask_b32_e32 v217, v167, v217, vcc
	v_fmac_f32_e32 v220, 0x3e0293ee, v14
	v_add_u32_e32 v168, -50, v166
	v_cmp_lt_i32_e32 vcc, -1, v168
	v_cndmask_b32_e32 v220, v167, v220, vcc
	v_fmac_f32_e32 v219, 0x3e0293ee, v15
	v_add_u32_e32 v168, -51, v166
	v_cmp_lt_i32_e32 vcc, -1, v168
	v_cndmask_b32_e32 v219, v167, v219, vcc
	s_waitcnt lgkmcnt(0)
; #define LAS __attribute__((address_space(3)))
; template <bool MOBA>
; __device__ __forceinline__ void attn_unit(LAS unsigned char* lds, const bf16_t* Qp, int ldq, const bf16_t* Kp, const bf16_t* Vp, int ldkv, bf16_t* Op, int ldo, int qt, const float* kmean, const float* relb, const int tid) {
;     ...
;                 const int qpos = qt * 128 + w * 16 + l15, kpos0 = kr0 + quad * 4;
; #pragma unroll
;                 for (int kt = 0; kt < 8; ++kt)
; #pragma unroll
;                     for (int i = 0; i < 4; ++i) { const int rel = qpos - (kpos0 + kt * 16 + i);
;                         const int ri = rel < 0 ? 0 : (rel > 127 ? 127 : rel); const float b = ((const LAS float*)(lds + AT_LUT))[ri];
;                         const bool valid = (j == own) ? (rel >= 0) : lsel;
;                         const float sv = valid ? sacc[kt][i] * sc2 + b : -INFINITY; sacc[kt][i] = sv; mx = fmaxf(mx, sv); }
	v_fmac_f32_e32 v222, 0x3e0293ee, v16
	v_add_u32_e32 v168, -64, v166
	v_cmp_lt_i32_e32 vcc, -1, v168
	v_cndmask_b32_e32 v222, v167, v222, vcc
	v_fmac_f32_e32 v221, 0x3e0293ee, v17
	v_add_u32_e32 v168, -65, v166
	v_cmp_lt_i32_e32 vcc, -1, v168
	v_cndmask_b32_e32 v221, v167, v221, vcc
	v_fmac_f32_e32 v224, 0x3e0293ee, v18
	v_add_u32_e32 v168, -66, v166
	v_cmp_lt_i32_e32 vcc, -1, v168
	v_cndmask_b32_e32 v224, v167, v224, vcc
	v_fmac_f32_e32 v223, 0x3e0293ee, v19
	v_add_u32_e32 v168, -67, v166
	v_cmp_lt_i32_e32 vcc, -1, v168
	v_cndmask_b32_e32 v223, v167, v223, vcc
	v_fmac_f32_e32 v229, 0x3e0293ee, v20
	v_add_u32_e32 v168, -80, v166
	v_cmp_lt_i32_e32 vcc, -1, v168
	v_cndmask_b32_e32 v229, v167, v229, vcc
	v_fmac_f32_e32 v225, 0x3e0293ee, v21
	v_add_u32_e32 v168, -81, v166
	v_cmp_lt_i32_e32 vcc, -1, v168
	v_cndmask_b32_e32 v225, v167, v225, vcc
	v_fmac_f32_e32 v231, 0x3e0293ee, v22
	v_add_u32_e32 v168, -82, v166
	v_cmp_lt_i32_e32 vcc, -1, v168
	v_cndmask_b32_e32 v231, v167, v231, vcc
	v_fmac_f32_e32 v230, 0x3e0293ee, v23
	v_add_u32_e32 v168, -83, v166
	v_cmp_lt_i32_e32 vcc, -1, v168
	v_cndmask_b32_e32 v230, v167, v230, vcc
	v_fmac_f32_e32 v233, 0x3e0293ee, v24
	v_add_u32_e32 v168, -96, v166
	v_cmp_lt_i32_e32 vcc, -1, v168
	v_cndmask_b32_e32 v233, v167, v233, vcc
	v_fmac_f32_e32 v232, 0x3e0293ee, v25
	v_add_u32_e32 v168, -97, v166
	v_cmp_lt_i32_e32 vcc, -1, v168
	v_cndmask_b32_e32 v232, v167, v232, vcc
	v_fmac_f32_e32 v235, 0x3e0293ee, v26
	v_add_u32_e32 v168, -98, v166
	v_cmp_lt_i32_e32 vcc, -1, v168
	v_cndmask_b32_e32 v235, v167, v235, vcc
	v_fmac_f32_e32 v234, 0x3e0293ee, v27
	v_add_u32_e32 v168, -99, v166
	v_cmp_lt_i32_e32 vcc, -1, v168
	v_cndmask_b32_e32 v234, v167, v234, vcc
	v_fmac_f32_e32 v237, 0x3e0293ee, v28
	v_add_u32_e32 v168, -112, v166
	v_cmp_lt_i32_e32 vcc, -1, v168
	v_cndmask_b32_e32 v237, v167, v237, vcc
	v_fmac_f32_e32 v236, 0x3e0293ee, v29
	v_add_u32_e32 v168, -113, v166
	v_cmp_lt_i32_e32 vcc, -1, v168
	v_cndmask_b32_e32 v236, v167, v236, vcc
	v_fmac_f32_e32 v238, 0x3e0293ee, v30
	v_add_u32_e32 v168, -114, v166
	v_cmp_lt_i32_e32 vcc, -1, v168
	v_cndmask_b32_e32 v238, v167, v238, vcc
	v_fmac_f32_e32 v127, 0x3e0293ee, v31
	v_add_u32_e32 v168, -115, v166
	v_cmp_lt_i32_e32 vcc, -1, v168
	v_cndmask_b32_e32 v127, v167, v127, vcc
	s_branch .LBB0_1246
.Llut_other:
	v_fmac_f32_e32 v204, 0x3e0293ee, v0
	v_cndmask_b32_e64 v204, v167, v204, s[10:11]
	v_fmac_f32_e32 v203, 0x3e0293ee, v1
	v_cndmask_b32_e64 v203, v167, v203, s[10:11]
	v_fmac_f32_e32 v207, 0x3e0293ee, v2
	v_cndmask_b32_e64 v207, v167, v207, s[10:11]
	v_fmac_f32_e32 v206, 0x3e0293ee, v3
	v_cndmask_b32_e64 v206, v167, v206, s[10:11]
	v_fmac_f32_e32 v209, 0x3e0293ee, v4
	v_cndmask_b32_e64 v209, v167, v209, s[10:11]
	v_fmac_f32_e32 v208, 0x3e0293ee, v5
	v_cndmask_b32_e64 v208, v167, v208, s[10:11]
	v_fmac_f32_e32 v211, 0x3e0293ee, v6
	v_cndmask_b32_e64 v211, v167, v211, s[10:11]
	v_fmac_f32_e32 v210, 0x3e0293ee, v7
	v_cndmask_b32_e64 v210, v167, v210, s[10:11]
	v_fmac_f32_e32 v213, 0x3e0293ee, v8
	v_cndmask_b32_e64 v213, v167, v213, s[10:11]
	v_fmac_f32_e32 v212, 0x3e0293ee, v9
	v_cndmask_b32_e64 v212, v167, v212, s[10:11]
	v_fmac_f32_e32 v215, 0x3e0293ee, v10
	v_cndmask_b32_e64 v215, v167, v215, s[10:11]
	v_fmac_f32_e32 v214, 0x3e0293ee, v11
	v_cndmask_b32_e64 v214, v167, v214, s[10:11]
	v_fmac_f32_e32 v218, 0x3e0293ee, v12
	v_cndmask_b32_e64 v218, v167, v218, s[10:11]
	v_fmac_f32_e32 v217, 0x3e0293ee, v13
	v_cndmask_b32_e64 v217, v167, v217, s[10:11]
	v_fmac_f32_e32 v220, 0x3e0293ee, v14
	v_cndmask_b32_e64 v220, v167, v220, s[10:11]
	v_fmac_f32_e32 v219, 0x3e0293ee, v15
	v_cndmask_b32_e64 v219, v167, v219, s[10:11]
	s_waitcnt lgkmcnt(0)
	v_fmac_f32_e32 v222, 0x3e0293ee, v16
	v_cndmask_b32_e64 v222, v167, v222, s[10:11]
	v_fmac_f32_e32 v221, 0x3e0293ee, v17
	v_cndmask_b32_e64 v221, v167, v221, s[10:11]
	v_fmac_f32_e32 v224, 0x3e0293ee, v18
	v_cndmask_b32_e64 v224, v167, v224, s[10:11]
	v_fmac_f32_e32 v223, 0x3e0293ee, v19
	v_cndmask_b32_e64 v223, v167, v223, s[10:11]
	v_fmac_f32_e32 v229, 0x3e0293ee, v20
	v_cndmask_b32_e64 v229, v167, v229, s[10:11]
	v_fmac_f32_e32 v225, 0x3e0293ee, v21
	v_cndmask_b32_e64 v225, v167, v225, s[10:11]
	v_fmac_f32_e32 v231, 0x3e0293ee, v22
	v_cndmask_b32_e64 v231, v167, v231, s[10:11]
	v_fmac_f32_e32 v230, 0x3e0293ee, v23
	v_cndmask_b32_e64 v230, v167, v230, s[10:11]
	v_fmac_f32_e32 v233, 0x3e0293ee, v24
	v_cndmask_b32_e64 v233, v167, v233, s[10:11]
	v_fmac_f32_e32 v232, 0x3e0293ee, v25
	v_cndmask_b32_e64 v232, v167, v232, s[10:11]
	v_fmac_f32_e32 v235, 0x3e0293ee, v26
	v_cndmask_b32_e64 v235, v167, v235, s[10:11]
	v_fmac_f32_e32 v234, 0x3e0293ee, v27
	v_cndmask_b32_e64 v234, v167, v234, s[10:11]
	v_fmac_f32_e32 v237, 0x3e0293ee, v28
	v_cndmask_b32_e64 v237, v167, v237, s[10:11]
	v_fmac_f32_e32 v236, 0x3e0293ee, v29
	v_cndmask_b32_e64 v236, v167, v236, s[10:11]
	v_fmac_f32_e32 v238, 0x3e0293ee, v30
	v_cndmask_b32_e64 v238, v167, v238, s[10:11]
	v_fmac_f32_e32 v127, 0x3e0293ee, v31
	v_cndmask_b32_e64 v127, v167, v127, s[10:11]
